# stack11 + combination of three exact edits: setprio pair removal in GEMM MFMA runs, ticket use-site waits removed, 64B-aligned hot loop heads
# baseline (speedup 1.0000x reference)
; __device__ __forceinline__ int crow(int r, int hi) { return (r & 3) + 8 * (r >> 2) + 4 * hi; }
; #define ATT_LOAD(t, S) do { const int tl_ = (t) < u_hi ? (t) : u_hi;     \
;         k##S = *(const u32x4*)(kg + (size_t)tl_ * 64 * 512); v##S = *(const u32x4*)(vg + (size_t)tl_ * 64 * 512); \
;         if (TYPE == 1) k2##S = *(const u32x4*)(krg + (size_t)tl_ * 64 * 32); if (TYPE == 0) cb##S = cg_[tl_ * 64]; } while (0)
; template <int TYPE, int ND0, int KSTR> __device__ __forceinline__ void tile(LAS unsigned char* lds, int buf, int t, int w_lo, int w_hi, int n, int qrel, int lane, int r32, int hi,
;         const bf16x8 (&qr)[ND0], float& m_run, float& l_run, f32x16& o0, f32x16& o1, f32x16& negm) {
;     ...
;         if (t == w_hi) {
; #pragma unroll
;             for (int r = 0; r < 16; ++r) { const int kr_ = crow(r, hi); if (kr_ > qrel) p0[r] = -1e30f; if (kr_ + 32 > qrel) p1[r] = -1e30f; }
;         }
; template <int TYPE> __device__ __forceinline__ int unit(const P& p, LAS unsigned char* lds, int b, int h, int qb, int wave0, bool pre, unsigned nx, int G,
;         u32x4& kA, u32x4& vA, u32x4& k2A, float& cbA, u32x4& kB, u32x4& vB, u32x4& k2B, float& cbB) {
;     ...
;     float m_run = 0.f, l_run = 0.f; f32x16 o0 = {}, o1 = {};
;     f32x16 negm;
; #pragma unroll
;     for (int r = 0; r < 16; ++r) negm[r] = 0.f;
;     if (!pre) { ATT_LOAD(u_lo, A); ATT_LOAD(u_lo + 1, B); }
;     ATT_STORE(0, A);
;     __syncthreads();
;     const int qrel = 32 * (w & 1) + r32;
;     int t = u_lo;
.LBB0_656:
	s_or_b64 exec, exec, s[0:1]
	v_lshrrev_b32_e32 v244, 2, v230
	v_lshlrev_b32_e32 v218, 2, v13
	v_and_or_b32 v2, v244, 3, v218
	s_waitcnt vmcnt(2)
	v_mad_u32_u24 v239, v2, s27, 0
	v_and_b32_e32 v2, 16, v230
	v_and_or_b32 v2, v180, 12, v2
	v_and_or_b32 v0, s2, 32, v12
	v_lshlrev_b32_e32 v243, 1, v2
	v_or_b32_e32 v2, 32, v218
	v_cmp_gt_u32_e64 s[46:47], v2, v0
	v_or_b32_e32 v2, 33, v218
	v_cmp_gt_u32_e64 s[48:49], v2, v0
	v_or_b32_e32 v2, 2, v218
	v_cmp_gt_u32_e64 s[50:51], v2, v0
	v_or_b32_e32 v2, 34, v218
	v_cmp_gt_u32_e64 s[52:53], v2, v0
	v_or_b32_e32 v2, 3, v218
	v_cmp_gt_u32_e64 s[54:55], v2, v0
	v_or_b32_e32 v2, 35, v218
	v_cmp_gt_u32_e64 s[56:57], v2, v0
	v_or_b32_e32 v2, 8, v218
	v_cmp_gt_u32_e64 s[58:59], v2, v0
	v_or_b32_e32 v2, 40, v218
	v_cmp_gt_u32_e64 s[60:61], v2, v0
	v_or_b32_e32 v2, 9, v218
	v_cmp_gt_u32_e64 s[62:63], v2, v0
	v_or_b32_e32 v2, 41, v218
	v_cmp_gt_u32_e64 s[64:65], v2, v0
	v_or_b32_e32 v2, 10, v218
	v_cmp_gt_u32_e64 s[66:67], v2, v0
	v_or_b32_e32 v2, 42, v218
	v_cmp_gt_u32_e64 s[68:69], v2, v0
	v_or_b32_e32 v2, 11, v218
	v_cmp_gt_u32_e64 s[70:71], v2, v0
	v_or_b32_e32 v2, 43, v218
	v_cmp_gt_u32_e64 s[74:75], v2, v0
	v_or_b32_e32 v2, 16, v218
	v_cmp_gt_u32_e64 s[76:77], v2, v0
	v_or_b32_e32 v2, 48, v218
	v_cmp_gt_u32_e64 s[78:79], v2, v0
	v_or_b32_e32 v2, 17, v218
	v_cmp_gt_u32_e64 s[80:81], v2, v0
	v_or_b32_e32 v2, 49, v218
	v_cmp_gt_u32_e64 s[82:83], v2, v0
	v_or_b32_e32 v2, 18, v218
	v_cmp_gt_u32_e64 s[84:85], v2, v0
	v_or_b32_e32 v2, 50, v218
	v_cmp_gt_u32_e64 s[86:87], v2, v0
	v_or_b32_e32 v2, 19, v218
	v_cmp_gt_u32_e64 s[88:89], v2, v0
	v_or_b32_e32 v2, 51, v218
	v_cmp_gt_u32_e64 s[90:91], v2, v0
	v_or_b32_e32 v2, 24, v218
	v_cmp_gt_u32_e64 s[92:93], v2, v0
	v_or_b32_e32 v2, 56, v218
	v_cmp_gt_u32_e64 s[94:95], v2, v0
	v_or_b32_e32 v2, 25, v218
	s_movk_i32 s0, 0x90
	v_cmp_gt_u32_e64 s[96:97], v2, v0
	v_or_b32_e32 v2, 57, v218
	v_mad_u32_u24 v173, v12, s0, 0
	v_cmp_gt_u32_e64 s[0:1], v2, v0
	v_or_b32_e32 v2, 26, v218
	v_cmp_gt_u32_e64 s[4:5], v2, v0
	v_or_b32_e32 v2, 58, v218
	v_cmp_gt_u32_e64 s[6:7], v2, v0
	v_or_b32_e32 v2, 27, v218
	v_lshlrev_b32_e32 v245, 3, v14
	s_ashr_i32 s3, s3, 7
	s_lshl_b32 s25, s33, 2
	v_cmp_gt_u32_e64 s[8:9], v2, v0
	v_or_b32_e32 v2, 59, v218
	s_lshl_b32 s2, s28, 2
	v_mov_b32_e32 v14, v1
	v_mov_b32_e32 v15, v1
	v_lshlrev_b64 v[176:177], 9, v[10:11]
	s_add_i32 s41, s3, s25
	v_cmp_gt_u32_e64 s[42:43], v218, v0
	v_cmp_lt_u32_e64 s[38:39], v218, v0
	v_cmp_gt_u32_e64 s[72:73], v2, v0
	s_add_i32 s3, s3, s2
	v_mov_b32_e32 v0, v1
	v_mov_b32_e32 v2, v1
	v_mov_b32_e32 v3, v1
	v_mov_b32_e32 v4, v1
	v_mov_b32_e32 v5, v1
	v_mov_b32_e32 v6, v1
	v_mov_b32_e32 v7, v1
	v_mov_b32_e32 v8, v1
	v_mov_b32_e32 v9, v1
	v_mov_b32_e32 v10, v1
	v_mov_b32_e32 v11, v1
	v_mov_b32_e32 v12, v1
	v_mov_b32_e32 v13, v1
	v_mov_b64_e32 v[46:47], v[14:15]
	v_mov_b64_e32 v[30:31], v[14:15]
	v_mov_b64_e32 v[62:63], v[14:15]
	v_add_u32_e32 v231, 0, v172
	v_add_u32_e32 v246, s26, v250
	s_mov_b32 s28, 0
	s_sub_i32 s30, 0, s3
	v_mov_b32_e32 v178, 0
	s_mov_b32 s29, -2
	v_mov_b64_e32 v[44:45], v[12:13]
	v_mov_b64_e32 v[42:43], v[10:11]
	v_mov_b64_e32 v[40:41], v[8:9]
	v_mov_b64_e32 v[38:39], v[6:7]
	v_mov_b64_e32 v[36:37], v[4:5]
	v_mov_b64_e32 v[34:35], v[2:3]
	v_mov_b64_e32 v[32:33], v[0:1]
	v_mov_b64_e32 v[28:29], v[12:13]
	v_mov_b64_e32 v[26:27], v[10:11]
	v_mov_b64_e32 v[24:25], v[8:9]
	v_mov_b64_e32 v[22:23], v[6:7]
	v_mov_b64_e32 v[20:21], v[4:5]
	v_mov_b64_e32 v[18:19], v[2:3]
	v_mov_b64_e32 v[16:17], v[0:1]
	v_mov_b64_e32 v[60:61], v[12:13]
	v_mov_b64_e32 v[58:59], v[10:11]
	v_mov_b64_e32 v[56:57], v[8:9]
	v_mov_b64_e32 v[54:55], v[6:7]
	v_mov_b64_e32 v[52:53], v[4:5]
	v_mov_b64_e32 v[50:51], v[2:3]
	v_mov_b64_e32 v[48:49], v[0:1]
	v_mov_b32_e32 v181, 0
	s_waitcnt lgkmcnt(0)
	s_barrier
	.p2alignl 6, 3212836864

; #define ATT_LOAD(t, S) do { const int tl_ = (t) < u_hi ? (t) : u_hi;     \
;         k##S = *(const u32x4*)(kg + (size_t)tl_ * 64 * 512); v##S = *(const u32x4*)(vg + (size_t)tl_ * 64 * 512); \
;         if (TYPE == 1) k2##S = *(const u32x4*)(krg + (size_t)tl_ * 64 * 32); if (TYPE == 0) cb##S = cg_[tl_ * 64]; } while (0)
; template <int TYPE> __device__ __forceinline__ int unit(const P& p, LAS unsigned char* lds, int b, int h, int qb, int wave0, bool pre, unsigned nx, int G,
;         u32x4& kA, u32x4& vA, u32x4& k2A, float& cbA, u32x4& kB, u32x4& vB, u32x4& k2B, float& cbB) {
;     ...
;     float m_run = 0.f, l_run = 0.f; f32x16 o0 = {}, o1 = {};
;     f32x16 negm;
; #pragma unroll
;     for (int r = 0; r < 16; ++r) negm[r] = 0.f;
;     if (!pre) { ATT_LOAD(u_lo, A); ATT_LOAD(u_lo + 1, B); }
;     ATT_STORE(0, A);
;     __syncthreads();
;     const int qrel = 32 * (w & 1) + r32;
;     int t = u_lo;
.LBB0_703:
	s_or_b64 exec, exec, s[4:5]
	v_lshlrev_b32_e32 v218, 2, v3
	v_and_b32_e32 v178, 63, v226
	v_mad_u32_u24 v227, v2, s10, 0
	v_and_or_b32 v2, v6, 3, v218
	s_movk_i32 s4, 0xc0
	v_mad_u32_u24 v228, v2, s4, 0
	v_and_b32_e32 v2, 16, v226
	v_lshlrev_b32_e32 v3, 2, v178
	v_and_or_b32 v2, v3, 12, v2
	v_mov_b32_e32 v14, v1
	v_mov_b32_e32 v15, v1
	v_lshlrev_b32_e32 v231, 3, v4
	v_lshlrev_b32_e32 v230, 3, v5
	s_ashr_i32 s9, s2, 7
	s_lshl_b32 s2, s33, 2
	v_lshlrev_b32_e32 v229, 1, v2
	v_add_u32_e32 v225, 0, v0
	v_mov_b32_e32 v0, v1
	v_mov_b32_e32 v2, v1
	v_mov_b32_e32 v3, v1
	v_mov_b32_e32 v4, v1
	v_mov_b32_e32 v5, v1
	v_mov_b32_e32 v6, v1
	v_mov_b32_e32 v7, v1
	v_mov_b32_e32 v8, v1
	v_mov_b32_e32 v9, v1
	v_mov_b32_e32 v10, v1
	v_mov_b32_e32 v11, v1
	v_mov_b32_e32 v12, v1
	v_mov_b32_e32 v13, v1
	v_mov_b64_e32 v[46:47], v[14:15]
	v_mov_b64_e32 v[30:31], v[14:15]
	v_mov_b64_e32 v[62:63], v[14:15]
	s_lshl_b32 s8, s24, 6
	s_add_i32 s9, s9, s2
	v_add_u32_e32 v219, s26, v250
	s_mov_b32 s3, 0
	v_mov_b32_e32 v166, 0
	v_mov_b64_e32 v[44:45], v[12:13]
	v_mov_b64_e32 v[42:43], v[10:11]
	v_mov_b64_e32 v[40:41], v[8:9]
	v_mov_b64_e32 v[38:39], v[6:7]
	v_mov_b64_e32 v[36:37], v[4:5]
	v_mov_b64_e32 v[34:35], v[2:3]
	v_mov_b64_e32 v[32:33], v[0:1]
	v_mov_b64_e32 v[28:29], v[12:13]
	v_mov_b64_e32 v[26:27], v[10:11]
	v_mov_b64_e32 v[24:25], v[8:9]
	v_mov_b64_e32 v[22:23], v[6:7]
	v_mov_b64_e32 v[20:21], v[4:5]
	v_mov_b64_e32 v[18:19], v[2:3]
	v_mov_b64_e32 v[16:17], v[0:1]
	v_mov_b64_e32 v[60:61], v[12:13]
	v_mov_b64_e32 v[58:59], v[10:11]
	v_mov_b64_e32 v[56:57], v[8:9]
	v_mov_b64_e32 v[54:55], v[6:7]
	v_mov_b64_e32 v[52:53], v[4:5]
	v_mov_b64_e32 v[50:51], v[2:3]
	v_mov_b64_e32 v[48:49], v[0:1]
	v_mov_b32_e32 v171, 0
	s_waitcnt lgkmcnt(0)
	s_barrier
	.p2alignl 6, 3212836864
